# norm wave-sum via DPP row reductions; sample conv on idle CUs
# speedup vs baseline: 1.0855x; 1.0123x over previous
.Lbnd_done:
	s_or_b64 exec, exec, s[4:5]
	v_lshl_add_u32 v0, s84, 9, v241
	v_add_u32_e32 v0, 0x42000, v0
	s_mov_b32 s2, 0x5d800
	v_cmp_gt_i32_e32 vcc, s2, v0
	s_mov_b32 s2, 0x57fff
	v_cmp_lt_i32_e64 s[2:3], s2, v0
	s_and_b64 vcc, vcc, s[2:3]
	s_and_saveexec_b64 s[4:5], vcc
	s_cbranch_execz .LBB0_193
	s_load_dwordx4 s[8:11], s[54:55], 0xb8
	s_load_dwordx2 s[2:3], s[54:55], 0x30
	s_lshl_b32 s34, s40, 9
	s_add_u32 s6, s82, 0xd200000
	v_readlane_b32 s14, v253, 41
	s_addc_u32 s7, s83, 0
	s_mul_i32 s13, s14, 0x10800
	s_mul_hi_i32 s12, s14, 0x10800
	s_waitcnt lgkmcnt(0)
	s_add_u32 s8, s8, s13
	s_addc_u32 s9, s9, s12
	s_mul_i32 s13, s14, 0x5800
	s_mul_hi_i32 s12, s14, 0x5800
	s_add_u32 s10, s10, s13
	s_addc_u32 s11, s11, s12
	s_mul_i32 s12, s14, 0x580000
	s_mul_hi_i32 s13, s14, 0x580000
	s_add_u32 s12, s2, s12
	s_addc_u32 s13, s3, s13
	s_add_u32 s14, s10, 0x2c00
	s_addc_u32 s15, s11, 0
	s_add_u32 s16, s8, 0x2c00
	s_addc_u32 s17, s9, 0
	s_add_u32 s18, s8, 0x5800
	s_addc_u32 s19, s9, 0
	s_add_u32 s20, s8, 0x8400
	s_addc_u32 s21, s9, 0
	s_add_u32 s22, s8, 0xb000
	s_addc_u32 s23, s9, 0
	s_add_u32 s24, s8, 0xdc00
	v_mov_b32_e32 v98, 0
	s_addc_u32 s25, s9, 0
	v_lshlrev_b32_e32 v5, 3, v0
	s_lshl_b32 s35, s40, 12
	s_mov_b64 s[26:27], 0
	v_mov_b32_e32 v99, v98
	v_mov_b32_e32 v100, v98
	v_mov_b32_e32 v101, v98
	s_waitcnt vmcnt(0)
	v_mov_b32_e32 v86, v98
	v_mov_b32_e32 v87, v98
	v_mov_b32_e32 v88, v98
	v_mov_b32_e32 v89, v98
	v_mov_b32_e32 v106, v98
	v_mov_b32_e32 v107, v98
	v_mov_b32_e32 v108, v98
	v_mov_b32_e32 v109, v98
	v_mov_b32_e32 v102, v98
	v_mov_b32_e32 v103, v98
	v_mov_b32_e32 v104, v98
	v_mov_b32_e32 v105, v98
	s_branch .LBB0_185

.LBB0_595:
.LBB0_596:
	s_waitcnt vmcnt(3)
	v_pk_mul_f32 v[74:75], v[68:69], v[68:69]
	v_pk_mul_f32 v[76:77], v[66:67], v[66:67]
	s_waitcnt vmcnt(2)
	v_pk_mul_f32 v[70:71], v[64:65], v[64:65]
	v_pk_mul_f32 v[72:73], v[62:63], v[62:63]
	s_waitcnt vmcnt(0)
	v_pk_mov_b32 v[78:79], v[76:77], v[74:75] op_sel:[1,0]
	v_mov_b32_e32 v77, v75
	v_pk_add_f32 v[74:75], v[78:79], v[76:77]
	v_pk_mov_b32 v[76:77], v[72:73], v[70:71] op_sel:[1,0]
	v_mov_b32_e32 v73, v71
	v_pk_add_f32 v[70:71], v[76:77], v[72:73]
	v_pk_add_f32 v[74:75], v[74:75], v[74:75] op_sel_hi:[0,1]
	v_pk_add_f32 v[70:71], v[70:71], v[70:71] op_sel_hi:[0,1]
	v_mul_f32_e32 v70, v58, v58
	v_pk_fma_f32 v[72:73], v[58:59], v[58:59], v[70:71] op_sel_hi:[1,1,0]
	v_mul_f32_e32 v70, v60, v60
	v_pk_fma_f32 v[76:77], v[60:61], v[60:61], v[70:71] op_sel_hi:[1,1,0]
	v_mul_f32_e32 v72, v54, v54
	v_mul_f32_e32 v76, v55, v55
	v_mul_f32_e32 v74, v56, v56
	v_mul_f32_e32 v70, v57, v57
	v_pk_add_f32 v[72:73], v[72:73], v[76:77]
	v_pk_add_f32 v[70:71], v[74:75], v[70:71]
	s_nop 0
	v_pk_add_f32 v[70:71], v[72:73], v[70:71]
	v_add_f32_e32 v70, v70, v71
	s_nop 1
	v_add_f32_dpp v70, v70, v70 quad_perm:[1,0,3,2] row_mask:0xf bank_mask:0xf
	s_nop 1
	v_add_f32_dpp v70, v70, v70 quad_perm:[2,3,0,1] row_mask:0xf bank_mask:0xf
	s_nop 1
	v_add_f32_dpp v70, v70, v70 row_half_mirror row_mask:0xf bank_mask:0xf
	s_nop 1
	v_add_f32_dpp v70, v70, v70 row_mirror row_mask:0xf bank_mask:0xf
	s_nop 1
	v_add_f32_dpp v70, v70, v70 row_bcast:15 row_mask:0xa bank_mask:0xf
	s_nop 1
	v_add_f32_dpp v70, v70, v70 row_bcast:31 row_mask:0xc bank_mask:0xf
	s_nop 1
	v_readlane_b32 vcc_lo, v70, 63
	s_nop 1
	v_mov_b32_e32 v70, vcc_lo
	v_fmamk_f32 v70, v70, 0x3a800000, v232
	v_mul_f32_e32 v71, 0x4f800000, v70
	v_cmp_gt_f32_e32 vcc, s95, v70
	s_nop 1
	v_cndmask_b32_e32 v70, v70, v71, vcc
	v_sqrt_f32_e32 v71, v70
	s_nop 0
	v_add_u32_e32 v72, -1, v71
	v_fma_f32 v73, -v72, v71, v70
	v_cmp_ge_f32_e64 s[4:5], 0, v73
	v_add_u32_e32 v73, 1, v71
	s_nop 0
	v_cndmask_b32_e64 v72, v71, v72, s[4:5]
	v_fma_f32 v71, -v73, v71, v70
	v_cmp_lt_f32_e64 s[4:5], 0, v71
	s_nop 1
	v_cndmask_b32_e64 v71, v72, v73, s[4:5]
	v_mul_f32_e32 v72, 0x37800000, v71
	v_cndmask_b32_e32 v71, v71, v72, vcc
	v_cmp_class_f32_e32 vcc, v70, v231
	s_nop 1
	v_cndmask_b32_e32 v70, v71, v70, vcc
	v_div_scale_f32 v71, s[4:5], v70, v70, 1.0
	v_rcp_f32_e32 v72, v71
	s_mov_b64 s[4:5], -1
	v_fma_f32 v73, -v71, v72, 1.0
	v_fmac_f32_e32 v72, v73, v72
	v_div_scale_f32 v73, vcc, 1.0, v70, 1.0
	v_mul_f32_e32 v74, v73, v72
	v_fma_f32 v75, -v71, v74, v73
	v_fmac_f32_e32 v74, v75, v72
	v_fma_f32 v71, -v71, v74, v73
	v_div_fmas_f32 v71, v71, v72, v74
	v_div_fixup_f32 v70, v71, v70, 1.0
	v_mov_b32_e32 v71, v70
	s_and_b64 vcc, exec, s[2:3]
	v_lshl_add_u64 v[72:73], s[18:19], 0, v[0:1]
	v_pk_mul_f32 v[74:75], v[66:67], v[70:71]
	s_cbranch_vccnz .LBB0_598
	v_mov_b32_e32 v76, v70
	v_mov_b32_e32 v77, v70
	v_pk_mul_f32 v[78:79], v[68:69], v[76:77]
	v_pk_mul_f32 v[80:81], v[6:7], v[74:75]
	v_pk_mul_f32 v[78:79], v[8:9], v[78:79]
	v_pk_add_f32 v[82:83], v[44:45], 1.0 op_sel_hi:[1,0]
	v_pk_add_f32 v[84:85], v[42:43], 1.0 op_sel_hi:[1,0]
	v_pk_fma_f32 v[78:79], v[82:83], v[78:79], v[24:25]
	v_pk_fma_f32 v[80:81], v[84:85], v[80:81], v[22:23]
	v_pk_add_f32 v[82:83], v[38:39], 1.0 op_sel_hi:[1,0]
	v_cvt_pk_bf16_f32 v80, v80, v81
	v_cvt_pk_bf16_f32 v81, v78, v79
	v_pk_mul_f32 v[78:79], v[62:63], v[70:71]
	global_store_dwordx2 v[2:3], v[80:81], off offset:-1536
	global_store_dwordx4 v[72:73], v[66:69], off
	v_pk_mul_f32 v[78:79], v[10:11], v[78:79]
	v_pk_add_f32 v[80:81], v[40:41], 1.0 op_sel_hi:[1,0]
	v_pk_mul_f32 v[66:67], v[64:65], v[76:77]
	v_pk_fma_f32 v[78:79], v[82:83], v[78:79], v[26:27]
	v_pk_mul_f32 v[66:67], v[12:13], v[66:67]
	v_cvt_pk_bf16_f32 v78, v78, v79
	v_pk_add_f32 v[82:83], v[50:51], 1.0 op_sel_hi:[1,0]
	v_pk_fma_f32 v[66:67], v[80:81], v[66:67], v[28:29]
	v_pk_add_f32 v[80:81], v[52:53], 1.0 op_sel_hi:[1,0]
	v_cvt_pk_bf16_f32 v79, v66, v67
	global_store_dwordx2 v[2:3], v[78:79], off offset:-1024
	global_store_dwordx4 v[72:73], v[62:65], off offset:1024
	v_pk_mul_f32 v[66:67], v[60:61], v[76:77]
	v_pk_mul_f32 v[78:79], v[58:59], v[70:71]
	v_pk_mul_f32 v[66:67], v[16:17], v[66:67]
	v_pk_mul_f32 v[78:79], v[14:15], v[78:79]
	s_ashr_i32 s15, s14, 31
	v_pk_fma_f32 v[66:67], v[80:81], v[66:67], v[32:33]
	v_pk_fma_f32 v[78:79], v[82:83], v[78:79], v[30:31]
	s_lshl_b64 s[2:3], s[14:15], 12
	v_cvt_pk_bf16_f32 v78, v78, v79
	v_cvt_pk_bf16_f32 v79, v66, v67
	v_pk_mul_f32 v[66:67], v[56:57], v[76:77]
	v_pk_mul_f32 v[76:77], v[54:55], v[70:71]
	s_add_u32 s2, s8, s2
	v_pk_mul_f32 v[76:77], v[18:19], v[76:77]
	v_pk_add_f32 v[80:81], v[46:47], 1.0 op_sel_hi:[1,0]
	s_addc_u32 s3, s9, s3
	global_store_dwordx2 v[2:3], v[78:79], off offset:-512
	global_store_dwordx4 v[72:73], v[58:61], off offset:2048
	v_pk_mul_f32 v[66:67], v[20:21], v[66:67]
	v_pk_add_f32 v[78:79], v[48:49], 1.0 op_sel_hi:[1,0]
	v_pk_fma_f32 v[76:77], v[80:81], v[76:77], v[34:35]
	s_mov_b64 s[4:5], 0
	v_pk_fma_f32 v[66:67], v[78:79], v[66:67], v[36:37]
	v_cvt_pk_bf16_f32 v76, v76, v77
	s_nop 0
	v_cvt_pk_bf16_f32 v77, v66, v67
	global_store_dwordx2 v[2:3], v[76:77], off

.LBB0_619:
	s_nop 0
	v_add_f32_dpp v122, v122, v122 quad_perm:[1,0,3,2] row_mask:0xf bank_mask:0xf
	v_add_f32_dpp v121, v121, v121 quad_perm:[1,0,3,2] row_mask:0xf bank_mask:0xf
	s_nop 0
	v_add_f32_dpp v122, v122, v122 quad_perm:[2,3,0,1] row_mask:0xf bank_mask:0xf
	v_add_f32_dpp v121, v121, v121 quad_perm:[2,3,0,1] row_mask:0xf bank_mask:0xf
	s_nop 0
	v_add_f32_dpp v122, v122, v122 row_half_mirror row_mask:0xf bank_mask:0xf
	v_add_f32_dpp v121, v121, v121 row_half_mirror row_mask:0xf bank_mask:0xf
	s_nop 0
	v_add_f32_dpp v122, v122, v122 row_mirror row_mask:0xf bank_mask:0xf
	v_add_f32_dpp v121, v121, v121 row_mirror row_mask:0xf bank_mask:0xf
	s_nop 0
	v_add_f32_dpp v122, v122, v122 row_bcast:15 row_mask:0xa bank_mask:0xf
	v_add_f32_dpp v121, v121, v121 row_bcast:15 row_mask:0xa bank_mask:0xf
	s_nop 0
	v_add_f32_dpp v122, v122, v122 row_bcast:31 row_mask:0xc bank_mask:0xf
	v_add_f32_dpp v121, v121, v121 row_bcast:31 row_mask:0xc bank_mask:0xf
	s_nop 0
	s_nop 0
	v_readlane_b32 s6, v122, 63
	v_readlane_b32 s7, v121, 63
	s_nop 1
	v_mov_b32_e32 v120, s6
	v_mov_b32_e32 v121, s7
.LBB0_621:
	v_fmamk_f32 v120, v120, 0x3a800000, v232
	v_mul_f32_e32 v122, 0x4f800000, v120
	v_cmp_gt_f32_e32 vcc, s95, v120
	s_nop 1
	v_cndmask_b32_e32 v120, v120, v122, vcc
	v_sqrt_f32_e32 v122, v120
	s_nop 0
	v_add_u32_e32 v123, -1, v122
	v_fma_f32 v131, -v123, v122, v120
	v_add_u32_e32 v130, 1, v122
	v_cmp_ge_f32_e64 s[6:7], 0, v131
	s_nop 1
	v_cndmask_b32_e64 v123, v122, v123, s[6:7]
	v_fma_f32 v122, -v130, v122, v120
	v_cmp_lt_f32_e64 s[6:7], 0, v122
	s_nop 1
	v_cndmask_b32_e64 v122, v123, v130, s[6:7]
	v_mul_f32_e32 v123, 0x37800000, v122
	v_cndmask_b32_e32 v122, v122, v123, vcc
	v_cmp_class_f32_e32 vcc, v120, v231
	s_nop 1
	v_cndmask_b32_e32 v120, v122, v120, vcc
	v_div_scale_f32 v122, s[6:7], v120, v120, 1.0
	v_rcp_f32_e32 v123, v122
	s_mov_b64 s[6:7], -1
	v_fma_f32 v130, -v122, v123, 1.0
	v_fmac_f32_e32 v123, v130, v123
	v_div_scale_f32 v130, vcc, 1.0, v120, 1.0
	v_mul_f32_e32 v131, v130, v123
	v_fma_f32 v132, -v122, v131, v130
	v_fmac_f32_e32 v131, v132, v123
	v_fma_f32 v122, -v122, v131, v130
	v_div_fmas_f32 v122, v122, v123, v131
	v_div_fixup_f32 v122, v122, v120, 1.0
	v_mov_b32_e32 v123, v122
	v_pk_mul_f32 v[114:115], v[114:115], v[122:123] op_sel_hi:[1,0]
	v_pk_mul_f32 v[116:117], v[116:117], v[122:123] op_sel_hi:[1,0]
	v_pk_mul_f32 v[114:115], v[6:7], v[114:115]
	v_pk_mul_f32 v[116:117], v[8:9], v[116:117]
	s_and_b64 vcc, exec, s[2:3]
	v_pk_mul_f32 v[110:111], v[110:111], v[122:123]
	v_pk_mul_f32 v[106:107], v[106:107], v[122:123]
	v_pk_mul_f32 v[102:103], v[102:103], v[122:123]
	s_cbranch_vccz .LBB0_624
	s_andn2_b64 vcc, exec, s[6:7]
	s_cbranch_vccz .LBB0_625
